# v27 + SCAN_B hand-written fast path (no peel) A/B reference
# speedup vs baseline: 1.0272x; 1.0122x over previous
.LBB0_1177:
	s_add_i32 s29, s29, 1
	s_cmp_eq_u32 s29, 17
	s_waitcnt lgkmcnt(0)
	s_barrier
	s_cbranch_scc1 .LBB0_1189
.LBB0_1178:
	s_and_b64 s[14:15], s[4:5], exec
	s_cselect_b32 s98, 0, 1
	s_sub_u32 s98, s29, s98
	s_cmp_gt_u32 s98, 15
	s_cbranch_scc1 .LBB0_1177
	s_lshr_b32 s30, s98, 1
	s_bitcmp0_b32 s98, 0
	s_mov_b64 s[14:15], -1
	s_cbranch_scc1 .LBB0_1184
	s_waitcnt vmcnt(0)
	ds_read_b128 v[68:71], v185 offset:17152
	ds_read_b128 v[72:75], v185
	ds_read_b128 v[84:87], v185 offset:17184
	ds_read_b128 v[88:91], v185 offset:32
	s_sub_i32 s31, 7, s30
	s_and_b64 s[14:15], s[4:5], exec
	s_waitcnt lgkmcnt(2)
	v_mfma_f32_32x32x16_bf16 v[68:83], v[68:71], v[72:75], 0
	s_cselect_b32 s14, s30, s31
	s_cmp_gt_u32 s98, 7
	s_mov_b64 s[42:43], -1
	s_waitcnt lgkmcnt(0)
	v_mfma_f32_32x32x16_bf16 v[68:83], v[84:87], v[88:91], v[68:83]
	ds_read_b128 v[84:87], v185 offset:17216
	ds_read_b128 v[88:91], v185 offset:64
	ds_read_b128 v[92:95], v185 offset:17248
	ds_read_b128 v[96:99], v185 offset:96
	s_waitcnt lgkmcnt(2)
	v_mfma_f32_32x32x16_bf16 v[68:83], v[84:87], v[88:91], v[68:83]
	s_waitcnt lgkmcnt(0)
	v_mfma_f32_32x32x16_bf16 v[68:83], v[92:95], v[96:99], v[68:83]
	ds_read_b128 v[84:87], v185 offset:17280
	ds_read_b128 v[88:91], v185 offset:128
	ds_read_b128 v[92:95], v185 offset:17312
	ds_read_b128 v[96:99], v185 offset:160
	s_waitcnt lgkmcnt(2)
	v_mfma_f32_32x32x16_bf16 v[68:83], v[84:87], v[88:91], v[68:83]
	s_waitcnt lgkmcnt(0)
	v_mfma_f32_32x32x16_bf16 v[68:83], v[92:95], v[96:99], v[68:83]
	ds_read_b128 v[84:87], v185 offset:17344
	ds_read_b128 v[88:91], v185 offset:192
	ds_read_b128 v[92:95], v185 offset:17376
	ds_read_b128 v[96:99], v185 offset:224
	s_waitcnt lgkmcnt(2)
	v_mfma_f32_32x32x16_bf16 v[68:83], v[84:87], v[88:91], v[68:83]
	ds_read_b64_tr_b16 v[84:85], v186 offset:36096
	ds_read_b64_tr_b16 v[86:87], v186 offset:38656
	ds_read_b64_tr_b16 v[88:89], v186 offset:41216
	ds_read_b64_tr_b16 v[90:91], v186 offset:43776
	s_waitcnt lgkmcnt(4)
	v_mfma_f32_32x32x16_bf16 v[68:83], v[92:95], v[96:99], v[68:83]
	v_add_u32_e32 v96, 0x2000, v187
	s_nop 10
	v_cvt_pk_bf16_f32 v68, v68, v69
	v_cvt_pk_bf16_f32 v69, v70, v71
	v_cvt_pk_bf16_f32 v70, v72, v73
	v_cvt_pk_bf16_f32 v71, v74, v75
	v_and_b32_e32 v68, v149, v68
	v_and_b32_e32 v69, v151, v69
	v_and_b32_e32 v70, v153, v70
	v_and_b32_e32 v71, v155, v71
	v_cvt_pk_bf16_f32 v72, v76, v77
	v_cvt_pk_bf16_f32 v93, v78, v79
	v_cvt_pk_bf16_f32 v94, v80, v81
	v_cvt_pk_bf16_f32 v95, v82, v83
	v_and_b32_e32 v92, v157, v72
	s_waitcnt lgkmcnt(2)
	v_mfma_f32_32x32x16_bf16 v[68:83], v[68:71], v[84:87], 0
	v_and_b32_e32 v93, v159, v93
	v_and_b32_e32 v94, v161, v94
	v_and_b32_e32 v95, v163, v95
	ds_read2_b64 v[84:87], v96 offset0:64 offset1:66
	s_waitcnt lgkmcnt(1)
	v_mfma_f32_32x32x16_bf16 v[68:83], v[92:95], v[88:91], v[68:83]
	v_cvt_pk_bf16_f32 v88, v4, v5
	v_cvt_pk_bf16_f32 v89, v6, v7
	v_cvt_pk_bf16_f32 v90, v8, v9
	v_cvt_pk_bf16_f32 v91, v10, v11
	s_waitcnt lgkmcnt(0)
	s_nop 0
	v_mfma_f32_32x32x16_bf16 v[68:83], v[84:87], v[88:91], v[68:83]
	ds_read2_b64 v[84:87], v96 offset0:68 offset1:70
	v_cvt_pk_bf16_f32 v88, v12, v13
	v_cvt_pk_bf16_f32 v89, v14, v15
	v_cvt_pk_bf16_f32 v90, v16, v17
	v_cvt_pk_bf16_f32 v91, v18, v19
	s_waitcnt lgkmcnt(0)
	s_nop 0
	v_mfma_f32_32x32x16_bf16 v[68:83], v[84:87], v[88:91], v[68:83]
	ds_read2_b64 v[84:87], v96 offset0:72 offset1:74
	v_cvt_pk_bf16_f32 v88, v52, v53
	v_cvt_pk_bf16_f32 v89, v54, v55
	v_cvt_pk_bf16_f32 v90, v56, v57
	v_cvt_pk_bf16_f32 v91, v58, v59
	s_waitcnt lgkmcnt(0)
	s_nop 0
	v_mfma_f32_32x32x16_bf16 v[68:83], v[84:87], v[88:91], v[68:83]
	ds_read2_b64 v[84:87], v96 offset0:76 offset1:78
	v_cvt_pk_bf16_f32 v88, v60, v61
	v_cvt_pk_bf16_f32 v89, v62, v63
	v_cvt_pk_bf16_f32 v90, v64, v65
	v_cvt_pk_bf16_f32 v91, v66, v67
	s_waitcnt lgkmcnt(0)
	s_nop 0
	v_mfma_f32_32x32x16_bf16 v[68:83], v[84:87], v[88:91], v[68:83]
	ds_read2_b64 v[84:87], v96 offset0:80 offset1:82
	v_cvt_pk_bf16_f32 v88, v36, v37
	v_cvt_pk_bf16_f32 v89, v38, v39
	v_cvt_pk_bf16_f32 v90, v40, v41
	v_cvt_pk_bf16_f32 v91, v42, v43
	s_waitcnt lgkmcnt(0)
	s_nop 0
	v_mfma_f32_32x32x16_bf16 v[68:83], v[84:87], v[88:91], v[68:83]
	ds_read2_b64 v[84:87], v96 offset0:84 offset1:86
	v_cvt_pk_bf16_f32 v88, v44, v45
	v_cvt_pk_bf16_f32 v89, v46, v47
	v_cvt_pk_bf16_f32 v90, v48, v49
	v_cvt_pk_bf16_f32 v91, v50, v51
	s_waitcnt lgkmcnt(0)
	s_nop 0
	v_mfma_f32_32x32x16_bf16 v[68:83], v[84:87], v[88:91], v[68:83]
	ds_read2_b64 v[84:87], v96 offset0:88 offset1:90
	v_cvt_pk_bf16_f32 v88, v20, v21
	v_cvt_pk_bf16_f32 v89, v22, v23
	v_cvt_pk_bf16_f32 v90, v24, v25
	v_cvt_pk_bf16_f32 v91, v26, v27
	s_waitcnt lgkmcnt(0)
	s_nop 0
	v_mfma_f32_32x32x16_bf16 v[68:83], v[84:87], v[88:91], v[68:83]
	ds_read2_b64 v[84:87], v96 offset0:92 offset1:94
	v_cvt_pk_bf16_f32 v88, v28, v29
	v_cvt_pk_bf16_f32 v89, v30, v31
	v_cvt_pk_bf16_f32 v90, v32, v33
	v_cvt_pk_bf16_f32 v91, v34, v35
	s_waitcnt lgkmcnt(0)
	s_nop 0
	v_mfma_f32_32x32x16_bf16 v[68:83], v[84:87], v[88:91], v[68:83]
	s_cbranch_scc1 .LBB0_1181
	s_mov_b64 s[42:43], 0

.LBB0_1187:
	s_or_b64 exec, exec, s[14:15]
	s_cmp_gt_u32 s98, 13
	s_cbranch_scc1 .LBB0_1177
	s_lshl_b32 s30, s30, 5
	s_add_i32 s31, s30, 32
	s_sub_i32 s33, 0xc7, s30
	s_and_b64 s[14:15], s[4:5], exec
	s_cselect_b32 s14, s31, s33
	s_add_i32 s14, s14, s44
	s_ashr_i32 s15, s14, 31
	s_lshl_b64 s[14:15], s[14:15], 11
	s_or_b64 s[14:15], s[14:15], s[38:39]
	v_lshl_add_u64 v[68:69], v[2:3], 0, s[14:15]
	s_sub_i32 s33, 0xc6, s30
	s_add_i32 s34, s30, 33
	global_load_dword v169, v[68:69], off
	v_lshl_add_u64 v[68:69], v[164:165], 0, s[14:15]
	s_and_b64 s[14:15], s[4:5], exec
	s_cselect_b32 s14, s34, s33
	s_add_i32 s14, s14, s44
	s_ashr_i32 s15, s14, 31
	s_lshl_b64 s[14:15], s[14:15], 11
	s_or_b64 s[14:15], s[14:15], s[38:39]
	global_load_dword v170, v[68:69], off
	v_lshl_add_u64 v[68:69], v[2:3], 0, s[14:15]
	s_sub_i32 s33, 0xc5, s30
	s_add_i32 s34, s30, 34
	global_load_dword v171, v[68:69], off
	v_lshl_add_u64 v[68:69], v[164:165], 0, s[14:15]
	s_and_b64 s[14:15], s[4:5], exec
	s_cselect_b32 s14, s34, s33
	s_add_i32 s14, s14, s44
	s_ashr_i32 s15, s14, 31
	s_lshl_b64 s[14:15], s[14:15], 11
	s_or_b64 s[14:15], s[14:15], s[38:39]
	global_load_dword v172, v[68:69], off
	v_lshl_add_u64 v[68:69], v[2:3], 0, s[14:15]
	s_sub_i32 s33, 0xc4, s30
	s_add_i32 s34, s30, 35
	global_load_dword v173, v[68:69], off
	v_lshl_add_u64 v[68:69], v[164:165], 0, s[14:15]
	s_and_b64 s[14:15], s[4:5], exec
	s_cselect_b32 s14, s34, s33
	s_add_i32 s14, s14, s44
	s_ashr_i32 s15, s14, 31
	s_lshl_b64 s[14:15], s[14:15], 11
	s_or_b64 s[14:15], s[14:15], s[38:39]
	global_load_dword v174, v[68:69], off
	v_lshl_add_u64 v[68:69], v[2:3], 0, s[14:15]
	s_sub_i32 s33, 0xc3, s30
	s_add_i32 s34, s30, 36
	global_load_dword v175, v[68:69], off
	v_lshl_add_u64 v[68:69], v[164:165], 0, s[14:15]
	s_and_b64 s[14:15], s[4:5], exec
	s_cselect_b32 s14, s34, s33
	s_add_i32 s14, s14, s44
	s_ashr_i32 s15, s14, 31
	s_lshl_b64 s[14:15], s[14:15], 11
	s_or_b64 s[14:15], s[14:15], s[38:39]
	global_load_dword v176, v[68:69], off
	v_lshl_add_u64 v[68:69], v[2:3], 0, s[14:15]
	s_sub_i32 s33, 0xc2, s30
	s_add_i32 s34, s30, 37
	global_load_dword v177, v[68:69], off
	v_lshl_add_u64 v[68:69], v[164:165], 0, s[14:15]
	s_and_b64 s[14:15], s[4:5], exec
	s_cselect_b32 s14, s34, s33
	s_add_i32 s14, s14, s44
	s_ashr_i32 s15, s14, 31
	s_lshl_b64 s[14:15], s[14:15], 11
	s_or_b64 s[14:15], s[14:15], s[38:39]
	global_load_dword v178, v[68:69], off
	v_lshl_add_u64 v[68:69], v[2:3], 0, s[14:15]
	s_sub_i32 s33, 0xc1, s30
	s_add_i32 s34, s30, 38
	global_load_dword v181, v[68:69], off
	v_lshl_add_u64 v[68:69], v[164:165], 0, s[14:15]
	s_and_b64 s[14:15], s[4:5], exec
	s_cselect_b32 s14, s34, s33
	s_add_i32 s14, s14, s44
	s_ashr_i32 s15, s14, 31
	s_lshl_b64 s[14:15], s[14:15], 11
	s_or_b64 s[14:15], s[14:15], s[38:39]
	global_load_dword v182, v[68:69], off
	v_lshl_add_u64 v[68:69], v[2:3], 0, s[14:15]
	s_sub_i32 s33, 0xc0, s30
	s_add_i32 s30, s30, 39
	global_load_dword v183, v[68:69], off
	v_lshl_add_u64 v[68:69], v[164:165], 0, s[14:15]
	s_and_b64 s[14:15], s[4:5], exec
	s_cselect_b32 s14, s30, s33
	s_add_i32 s14, s14, s44
	s_ashr_i32 s15, s14, 31
	s_lshl_b64 s[14:15], s[14:15], 11
	s_or_b64 s[14:15], s[14:15], s[38:39]
	global_load_dword v184, v[68:69], off
	v_lshl_add_u64 v[68:69], v[2:3], 0, s[14:15]
	global_load_dword v194, v[68:69], off
	v_lshl_add_u64 v[68:69], v[164:165], 0, s[14:15]
	s_and_b64 s[14:15], s[4:5], exec
	s_cselect_b32 s14, s31, s33
	s_add_i32 s14, s14, s44
	s_ashr_i32 s15, s14, 31
	s_lshl_b64 s[14:15], s[14:15], 11
	global_load_dword v199, v[68:69], off
	v_lshl_add_u64 v[68:69], v[166:167], 0, s[14:15]
	global_load_dwordx4 v[132:135], v[68:69], off offset:16
	global_load_dwordx4 v[136:139], v[68:69], off
	v_readlane_b32 s34, v249, 9
	s_branch .LBB0_1177

.LBB0_1268:
	s_cmp_lt_i32 s58, 13
	s_cselect_b64 s[6:7], -1, 0
	s_and_b64 s[4:5], s[6:7], s[4:5]
	s_andn2_b64 vcc, exec, s[4:5]
	s_cbranch_vccnz .LBB0_1275
	v_readlane_b32 s8, v249, 2
	s_nop 0
	s_cmpk_lg_i32 s8, 0x100
	s_cbranch_scc1 .Lscanb_generic
	v_lshl_or_b32 v1, s94, 9, v0
	s_mov_b32 s12, 0xffff8000
	s_mov_b32 s13, 0xfffffe00
	s_cmpk_lt_u32 s94, 0x80
	s_cselect_b32 s8, 0x8000, s12
	s_cselect_b32 s9, 0x200, s13
	s_cselect_b32 s10, 0, 0x78000
	s_cselect_b32 s11, 0, 0x1e00
	v_lshrrev_b32_e32 v2, 11, v1
	v_and_b32_e32 v3, 0x7ff, v1
	v_lshlrev_b32_e32 v3, 3, v3
	v_bfe_u32 v4, v2, 3, 2
	v_and_b32_e32 v5, 7, v2
	v_lshrrev_b32_e32 v6, 5, v2
	v_bfe_u32 v7, v3, 10, 2
	v_bfe_u32 v8, v3, 9, 1
	v_and_b32_e32 v9, 8, v3
	v_lshlrev_b32_e32 v10, 5, v7
	v_lshl_add_u32 v10, v8, 2, v10
	v_lshl_add_u32 v10, v9, 1, v10
	v_bfe_u32 v11, v3, 12, 2
	v_bfe_u32 v12, v3, 4, 5
	v_lshl_add_u32 v11, v11, 5, v12
	v_lshl_add_u32 v13, v4, 1, v6
	v_lshl_add_u32 v13, v13, 3, v5
	v_lshl_add_u32 v13, v13, 7, v10
	v_lshl_add_u32 v13, v13, 7, v11
	v_lshlrev_b32_e32 v13, 2, v13
	v_add_u32_e32 v14, 0x1000, v13
	global_load_dword v16, v13, s[40:41] offset:0 nt
	global_load_dword v17, v13, s[40:41] offset:512 nt
	global_load_dword v18, v13, s[40:41] offset:1024 nt
	global_load_dword v19, v13, s[40:41] offset:1536 nt
	global_load_dword v20, v14, s[40:41] offset:0 nt
	global_load_dword v21, v14, s[40:41] offset:512 nt
	global_load_dword v22, v14, s[40:41] offset:1024 nt
	global_load_dword v23, v14, s[40:41] offset:1536 nt
	v_lshlrev_b32_e32 v15, 19, v2
	v_lshl_add_u32 v15, v3, 1, v15
	v_add_u32_e32 v15, s10, v15
	v_lshlrev_b32_e32 v12, 13, v2
	v_lshl_add_u32 v12, v10, 2, v12
	v_add_u32_e32 v12, s11, v12
	v_mov_b32_e32 v11, v15
	v_add_u32_e32 v15, s8, v15
	v_add_u32_e32 v12, s9, v12
	global_load_dwordx4 v[24:27], v15, s[96:97]
	global_load_dwordx4 v[28:31], v12, s[26:27]
	global_load_dwordx4 v[32:35], v12, s[26:27] offset:32
	v_add_u32_e32 v15, s8, v15
	v_add_u32_e32 v12, s9, v12
	global_load_dwordx4 v[36:39], v15, s[96:97]
	global_load_dwordx4 v[40:43], v12, s[26:27]
	global_load_dwordx4 v[44:47], v12, s[26:27] offset:32
	v_add_u32_e32 v15, s8, v15
	v_add_u32_e32 v12, s9, v12
	global_load_dwordx4 v[48:51], v15, s[96:97]
	global_load_dwordx4 v[52:55], v12, s[26:27]
	global_load_dwordx4 v[56:59], v12, s[26:27] offset:32
	v_add_u32_e32 v15, s8, v15
	v_add_u32_e32 v12, s9, v12
	global_load_dwordx4 v[60:63], v15, s[96:97]
	global_load_dwordx4 v[64:67], v12, s[26:27]
	global_load_dwordx4 v[68:71], v12, s[26:27] offset:32
	v_add_u32_e32 v15, s8, v15
	v_add_u32_e32 v12, s9, v12
	global_load_dwordx4 v[72:75], v15, s[96:97]
	global_load_dwordx4 v[76:79], v12, s[26:27]
	global_load_dwordx4 v[80:83], v12, s[26:27] offset:32
	v_add_u32_e32 v15, s8, v15
	v_add_u32_e32 v12, s9, v12
	global_load_dwordx4 v[84:87], v15, s[96:97]
	global_load_dwordx4 v[88:91], v12, s[26:27]
	global_load_dwordx4 v[92:95], v12, s[26:27] offset:32
	v_add_u32_e32 v15, s8, v15
	v_add_u32_e32 v12, s9, v12
	global_load_dwordx4 v[96:99], v15, s[96:97]
	global_load_dwordx4 v[100:103], v12, s[26:27]
	global_load_dwordx4 v[104:107], v12, s[26:27] offset:32
	v_add_u32_e32 v15, s8, v15
	v_add_u32_e32 v12, s9, v12
	global_load_dwordx4 v[108:111], v15, s[96:97]
	global_load_dwordx4 v[112:115], v12, s[26:27]
	global_load_dwordx4 v[116:119], v12, s[26:27] offset:32
	v_add_u32_e32 v15, s8, v15
	v_add_u32_e32 v12, s9, v12
	global_load_dwordx4 v[120:123], v15, s[96:97]
	global_load_dwordx4 v[124:127], v12, s[26:27]
	global_load_dwordx4 v[128:131], v12, s[26:27] offset:32
	v_add_u32_e32 v15, s8, v15
	v_add_u32_e32 v12, s9, v12
	global_load_dwordx4 v[132:135], v15, s[96:97]
	global_load_dwordx4 v[136:139], v12, s[26:27]
	global_load_dwordx4 v[140:143], v12, s[26:27] offset:32
	v_add_u32_e32 v15, s8, v15
	v_add_u32_e32 v12, s9, v12
	global_load_dwordx4 v[144:147], v15, s[96:97]
	global_load_dwordx4 v[148:151], v12, s[26:27]
	global_load_dwordx4 v[152:155], v12, s[26:27] offset:32
	v_add_u32_e32 v15, s8, v15
	v_add_u32_e32 v12, s9, v12
	global_load_dwordx4 v[156:159], v15, s[96:97]
	global_load_dwordx4 v[160:163], v12, s[26:27]
	global_load_dwordx4 v[164:167], v12, s[26:27] offset:32
	v_add_u32_e32 v15, s8, v15
	v_add_u32_e32 v12, s9, v12
	global_load_dwordx4 v[168:171], v15, s[96:97]
	global_load_dwordx4 v[172:175], v12, s[26:27]
	global_load_dwordx4 v[176:179], v12, s[26:27] offset:32
	v_add_u32_e32 v15, s8, v15
	v_add_u32_e32 v12, s9, v12
	global_load_dwordx4 v[180:183], v15, s[96:97]
	global_load_dwordx4 v[184:187], v12, s[26:27]
	global_load_dwordx4 v[188:191], v12, s[26:27] offset:32
	v_add_u32_e32 v15, s8, v15
	v_add_u32_e32 v12, s9, v12
	global_load_dwordx4 v[192:195], v15, s[96:97]
	global_load_dwordx4 v[196:199], v12, s[26:27]
	global_load_dwordx4 v[200:203], v12, s[26:27] offset:32
	s_waitcnt vmcnt(45)
	v_cvt_pk_bf16_f32 v4, v16, v17
	v_cvt_pk_bf16_f32 v5, v18, v19
	v_cvt_pk_bf16_f32 v6, v20, v21
	v_cvt_pk_bf16_f32 v7, v22, v23
	global_store_dwordx4 v11, v[4:7], s[96:97]
	s_waitcnt vmcnt(43)
	v_add_u32_e32 v11, s8, v11
	v_lshlrev_b32_e32 v8, 16, v24
	v_and_b32_e32 v9, 0xffff0000, v24
	v_fma_f32 v16, v28, v16, v8
	v_fma_f32 v17, v29, v17, v9
	v_lshlrev_b32_e32 v8, 16, v25
	v_and_b32_e32 v9, 0xffff0000, v25
	v_fma_f32 v18, v30, v18, v8
	v_fma_f32 v19, v31, v19, v9
	v_lshlrev_b32_e32 v8, 16, v26
	v_and_b32_e32 v9, 0xffff0000, v26
	v_fma_f32 v20, v32, v20, v8
	v_fma_f32 v21, v33, v21, v9
	v_lshlrev_b32_e32 v8, 16, v27
	v_and_b32_e32 v9, 0xffff0000, v27
	v_fma_f32 v22, v34, v22, v8
	v_fma_f32 v23, v35, v23, v9
	v_cvt_pk_bf16_f32 v212, v16, v17
	v_cvt_pk_bf16_f32 v213, v18, v19
	v_cvt_pk_bf16_f32 v214, v20, v21
	v_cvt_pk_bf16_f32 v215, v22, v23
	global_store_dwordx4 v11, v[212:215], s[96:97]
	s_waitcnt vmcnt(41)
	v_add_u32_e32 v11, s8, v11
	v_lshlrev_b32_e32 v8, 16, v36
	v_and_b32_e32 v9, 0xffff0000, v36
	v_fma_f32 v16, v40, v16, v8
	v_fma_f32 v17, v41, v17, v9
	v_lshlrev_b32_e32 v8, 16, v37
	v_and_b32_e32 v9, 0xffff0000, v37
	v_fma_f32 v18, v42, v18, v8
	v_fma_f32 v19, v43, v19, v9
	v_lshlrev_b32_e32 v8, 16, v38
	v_and_b32_e32 v9, 0xffff0000, v38
	v_fma_f32 v20, v44, v20, v8
	v_fma_f32 v21, v45, v21, v9
	v_lshlrev_b32_e32 v8, 16, v39
	v_and_b32_e32 v9, 0xffff0000, v39
	v_fma_f32 v22, v46, v22, v8
	v_fma_f32 v23, v47, v23, v9
	v_cvt_pk_bf16_f32 v4, v16, v17
	v_cvt_pk_bf16_f32 v5, v18, v19
	v_cvt_pk_bf16_f32 v6, v20, v21
	v_cvt_pk_bf16_f32 v7, v22, v23
	global_store_dwordx4 v11, v[4:7], s[96:97]
	s_waitcnt vmcnt(39)
	v_add_u32_e32 v11, s8, v11
	v_lshlrev_b32_e32 v8, 16, v48
	v_and_b32_e32 v9, 0xffff0000, v48
	v_fma_f32 v16, v52, v16, v8
	v_fma_f32 v17, v53, v17, v9
	v_lshlrev_b32_e32 v8, 16, v49
	v_and_b32_e32 v9, 0xffff0000, v49
	v_fma_f32 v18, v54, v18, v8
	v_fma_f32 v19, v55, v19, v9
	v_lshlrev_b32_e32 v8, 16, v50
	v_and_b32_e32 v9, 0xffff0000, v50
	v_fma_f32 v20, v56, v20, v8
	v_fma_f32 v21, v57, v21, v9
	v_lshlrev_b32_e32 v8, 16, v51
	v_and_b32_e32 v9, 0xffff0000, v51
	v_fma_f32 v22, v58, v22, v8
	v_fma_f32 v23, v59, v23, v9
	v_cvt_pk_bf16_f32 v212, v16, v17
	v_cvt_pk_bf16_f32 v213, v18, v19
	v_cvt_pk_bf16_f32 v214, v20, v21
	v_cvt_pk_bf16_f32 v215, v22, v23
	global_store_dwordx4 v11, v[212:215], s[96:97]
	s_waitcnt vmcnt(37)
	v_add_u32_e32 v11, s8, v11
	v_lshlrev_b32_e32 v8, 16, v60
	v_and_b32_e32 v9, 0xffff0000, v60
	v_fma_f32 v16, v64, v16, v8
	v_fma_f32 v17, v65, v17, v9
	v_lshlrev_b32_e32 v8, 16, v61
	v_and_b32_e32 v9, 0xffff0000, v61
	v_fma_f32 v18, v66, v18, v8
	v_fma_f32 v19, v67, v19, v9
	v_lshlrev_b32_e32 v8, 16, v62
	v_and_b32_e32 v9, 0xffff0000, v62
	v_fma_f32 v20, v68, v20, v8
	v_fma_f32 v21, v69, v21, v9
	v_lshlrev_b32_e32 v8, 16, v63
	v_and_b32_e32 v9, 0xffff0000, v63
	v_fma_f32 v22, v70, v22, v8
	v_fma_f32 v23, v71, v23, v9
	v_cvt_pk_bf16_f32 v4, v16, v17
	v_cvt_pk_bf16_f32 v5, v18, v19
	v_cvt_pk_bf16_f32 v6, v20, v21
	v_cvt_pk_bf16_f32 v7, v22, v23
	global_store_dwordx4 v11, v[4:7], s[96:97]
	s_waitcnt vmcnt(35)
	v_add_u32_e32 v11, s8, v11
	v_lshlrev_b32_e32 v8, 16, v72
	v_and_b32_e32 v9, 0xffff0000, v72
	v_fma_f32 v16, v76, v16, v8
	v_fma_f32 v17, v77, v17, v9
	v_lshlrev_b32_e32 v8, 16, v73
	v_and_b32_e32 v9, 0xffff0000, v73
	v_fma_f32 v18, v78, v18, v8
	v_fma_f32 v19, v79, v19, v9
	v_lshlrev_b32_e32 v8, 16, v74
	v_and_b32_e32 v9, 0xffff0000, v74
	v_fma_f32 v20, v80, v20, v8
	v_fma_f32 v21, v81, v21, v9
	v_lshlrev_b32_e32 v8, 16, v75
	v_and_b32_e32 v9, 0xffff0000, v75
	v_fma_f32 v22, v82, v22, v8
	v_fma_f32 v23, v83, v23, v9
	v_cvt_pk_bf16_f32 v212, v16, v17
	v_cvt_pk_bf16_f32 v213, v18, v19
	v_cvt_pk_bf16_f32 v214, v20, v21
	v_cvt_pk_bf16_f32 v215, v22, v23
	global_store_dwordx4 v11, v[212:215], s[96:97]
	s_waitcnt vmcnt(33)
	v_add_u32_e32 v11, s8, v11
	v_lshlrev_b32_e32 v8, 16, v84
	v_and_b32_e32 v9, 0xffff0000, v84
	v_fma_f32 v16, v88, v16, v8
	v_fma_f32 v17, v89, v17, v9
	v_lshlrev_b32_e32 v8, 16, v85
	v_and_b32_e32 v9, 0xffff0000, v85
	v_fma_f32 v18, v90, v18, v8
	v_fma_f32 v19, v91, v19, v9
	v_lshlrev_b32_e32 v8, 16, v86
	v_and_b32_e32 v9, 0xffff0000, v86
	v_fma_f32 v20, v92, v20, v8
	v_fma_f32 v21, v93, v21, v9
	v_lshlrev_b32_e32 v8, 16, v87
	v_and_b32_e32 v9, 0xffff0000, v87
	v_fma_f32 v22, v94, v22, v8
	v_fma_f32 v23, v95, v23, v9
	v_cvt_pk_bf16_f32 v4, v16, v17
	v_cvt_pk_bf16_f32 v5, v18, v19
	v_cvt_pk_bf16_f32 v6, v20, v21
	v_cvt_pk_bf16_f32 v7, v22, v23
	global_store_dwordx4 v11, v[4:7], s[96:97]
	s_waitcnt vmcnt(31)
	v_add_u32_e32 v11, s8, v11
	v_lshlrev_b32_e32 v8, 16, v96
	v_and_b32_e32 v9, 0xffff0000, v96
	v_fma_f32 v16, v100, v16, v8
	v_fma_f32 v17, v101, v17, v9
	v_lshlrev_b32_e32 v8, 16, v97
	v_and_b32_e32 v9, 0xffff0000, v97
	v_fma_f32 v18, v102, v18, v8
	v_fma_f32 v19, v103, v19, v9
	v_lshlrev_b32_e32 v8, 16, v98
	v_and_b32_e32 v9, 0xffff0000, v98
	v_fma_f32 v20, v104, v20, v8
	v_fma_f32 v21, v105, v21, v9
	v_lshlrev_b32_e32 v8, 16, v99
	v_and_b32_e32 v9, 0xffff0000, v99
	v_fma_f32 v22, v106, v22, v8
	v_fma_f32 v23, v107, v23, v9
	v_cvt_pk_bf16_f32 v212, v16, v17
	v_cvt_pk_bf16_f32 v213, v18, v19
	v_cvt_pk_bf16_f32 v214, v20, v21
	v_cvt_pk_bf16_f32 v215, v22, v23
	global_store_dwordx4 v11, v[212:215], s[96:97]
	s_waitcnt vmcnt(29)
	v_add_u32_e32 v11, s8, v11
	v_lshlrev_b32_e32 v8, 16, v108
	v_and_b32_e32 v9, 0xffff0000, v108
	v_fma_f32 v16, v112, v16, v8
	v_fma_f32 v17, v113, v17, v9
	v_lshlrev_b32_e32 v8, 16, v109
	v_and_b32_e32 v9, 0xffff0000, v109
	v_fma_f32 v18, v114, v18, v8
	v_fma_f32 v19, v115, v19, v9
	v_lshlrev_b32_e32 v8, 16, v110
	v_and_b32_e32 v9, 0xffff0000, v110
	v_fma_f32 v20, v116, v20, v8
	v_fma_f32 v21, v117, v21, v9
	v_lshlrev_b32_e32 v8, 16, v111
	v_and_b32_e32 v9, 0xffff0000, v111
	v_fma_f32 v22, v118, v22, v8
	v_fma_f32 v23, v119, v23, v9
	v_cvt_pk_bf16_f32 v4, v16, v17
	v_cvt_pk_bf16_f32 v5, v18, v19
	v_cvt_pk_bf16_f32 v6, v20, v21
	v_cvt_pk_bf16_f32 v7, v22, v23
	global_store_dwordx4 v11, v[4:7], s[96:97]
	s_waitcnt vmcnt(27)
	v_add_u32_e32 v11, s8, v11
	v_lshlrev_b32_e32 v8, 16, v120
	v_and_b32_e32 v9, 0xffff0000, v120
	v_fma_f32 v16, v124, v16, v8
	v_fma_f32 v17, v125, v17, v9
	v_lshlrev_b32_e32 v8, 16, v121
	v_and_b32_e32 v9, 0xffff0000, v121
	v_fma_f32 v18, v126, v18, v8
	v_fma_f32 v19, v127, v19, v9
	v_lshlrev_b32_e32 v8, 16, v122
	v_and_b32_e32 v9, 0xffff0000, v122
	v_fma_f32 v20, v128, v20, v8
	v_fma_f32 v21, v129, v21, v9
	v_lshlrev_b32_e32 v8, 16, v123
	v_and_b32_e32 v9, 0xffff0000, v123
	v_fma_f32 v22, v130, v22, v8
	v_fma_f32 v23, v131, v23, v9
	v_cvt_pk_bf16_f32 v212, v16, v17
	v_cvt_pk_bf16_f32 v213, v18, v19
	v_cvt_pk_bf16_f32 v214, v20, v21
	v_cvt_pk_bf16_f32 v215, v22, v23
	global_store_dwordx4 v11, v[212:215], s[96:97]
	s_waitcnt vmcnt(25)
	v_add_u32_e32 v11, s8, v11
	v_lshlrev_b32_e32 v8, 16, v132
	v_and_b32_e32 v9, 0xffff0000, v132
	v_fma_f32 v16, v136, v16, v8
	v_fma_f32 v17, v137, v17, v9
	v_lshlrev_b32_e32 v8, 16, v133
	v_and_b32_e32 v9, 0xffff0000, v133
	v_fma_f32 v18, v138, v18, v8
	v_fma_f32 v19, v139, v19, v9
	v_lshlrev_b32_e32 v8, 16, v134
	v_and_b32_e32 v9, 0xffff0000, v134
	v_fma_f32 v20, v140, v20, v8
	v_fma_f32 v21, v141, v21, v9
	v_lshlrev_b32_e32 v8, 16, v135
	v_and_b32_e32 v9, 0xffff0000, v135
	v_fma_f32 v22, v142, v22, v8
	v_fma_f32 v23, v143, v23, v9
	v_cvt_pk_bf16_f32 v4, v16, v17
	v_cvt_pk_bf16_f32 v5, v18, v19
	v_cvt_pk_bf16_f32 v6, v20, v21
	v_cvt_pk_bf16_f32 v7, v22, v23
	global_store_dwordx4 v11, v[4:7], s[96:97]
	s_waitcnt vmcnt(23)
	v_add_u32_e32 v11, s8, v11
	v_lshlrev_b32_e32 v8, 16, v144
	v_and_b32_e32 v9, 0xffff0000, v144
	v_fma_f32 v16, v148, v16, v8
	v_fma_f32 v17, v149, v17, v9
	v_lshlrev_b32_e32 v8, 16, v145
	v_and_b32_e32 v9, 0xffff0000, v145
	v_fma_f32 v18, v150, v18, v8
	v_fma_f32 v19, v151, v19, v9
	v_lshlrev_b32_e32 v8, 16, v146
	v_and_b32_e32 v9, 0xffff0000, v146
	v_fma_f32 v20, v152, v20, v8
	v_fma_f32 v21, v153, v21, v9
	v_lshlrev_b32_e32 v8, 16, v147
	v_and_b32_e32 v9, 0xffff0000, v147
	v_fma_f32 v22, v154, v22, v8
	v_fma_f32 v23, v155, v23, v9
	v_cvt_pk_bf16_f32 v212, v16, v17
	v_cvt_pk_bf16_f32 v213, v18, v19
	v_cvt_pk_bf16_f32 v214, v20, v21
	v_cvt_pk_bf16_f32 v215, v22, v23
	global_store_dwordx4 v11, v[212:215], s[96:97]
	s_waitcnt vmcnt(21)
	v_add_u32_e32 v11, s8, v11
	v_lshlrev_b32_e32 v8, 16, v156
	v_and_b32_e32 v9, 0xffff0000, v156
	v_fma_f32 v16, v160, v16, v8
	v_fma_f32 v17, v161, v17, v9
	v_lshlrev_b32_e32 v8, 16, v157
	v_and_b32_e32 v9, 0xffff0000, v157
	v_fma_f32 v18, v162, v18, v8
	v_fma_f32 v19, v163, v19, v9
	v_lshlrev_b32_e32 v8, 16, v158
	v_and_b32_e32 v9, 0xffff0000, v158
	v_fma_f32 v20, v164, v20, v8
	v_fma_f32 v21, v165, v21, v9
	v_lshlrev_b32_e32 v8, 16, v159
	v_and_b32_e32 v9, 0xffff0000, v159
	v_fma_f32 v22, v166, v22, v8
	v_fma_f32 v23, v167, v23, v9
	v_cvt_pk_bf16_f32 v4, v16, v17
	v_cvt_pk_bf16_f32 v5, v18, v19
	v_cvt_pk_bf16_f32 v6, v20, v21
	v_cvt_pk_bf16_f32 v7, v22, v23
	global_store_dwordx4 v11, v[4:7], s[96:97]
	s_waitcnt vmcnt(19)
	v_add_u32_e32 v11, s8, v11
	v_lshlrev_b32_e32 v8, 16, v168
	v_and_b32_e32 v9, 0xffff0000, v168
	v_fma_f32 v16, v172, v16, v8
	v_fma_f32 v17, v173, v17, v9
	v_lshlrev_b32_e32 v8, 16, v169
	v_and_b32_e32 v9, 0xffff0000, v169
	v_fma_f32 v18, v174, v18, v8
	v_fma_f32 v19, v175, v19, v9
	v_lshlrev_b32_e32 v8, 16, v170
	v_and_b32_e32 v9, 0xffff0000, v170
	v_fma_f32 v20, v176, v20, v8
	v_fma_f32 v21, v177, v21, v9
	v_lshlrev_b32_e32 v8, 16, v171
	v_and_b32_e32 v9, 0xffff0000, v171
	v_fma_f32 v22, v178, v22, v8
	v_fma_f32 v23, v179, v23, v9
	v_cvt_pk_bf16_f32 v212, v16, v17
	v_cvt_pk_bf16_f32 v213, v18, v19
	v_cvt_pk_bf16_f32 v214, v20, v21
	v_cvt_pk_bf16_f32 v215, v22, v23
	global_store_dwordx4 v11, v[212:215], s[96:97]
	s_waitcnt vmcnt(17)
	v_add_u32_e32 v11, s8, v11
	v_lshlrev_b32_e32 v8, 16, v180
	v_and_b32_e32 v9, 0xffff0000, v180
	v_fma_f32 v16, v184, v16, v8
	v_fma_f32 v17, v185, v17, v9
	v_lshlrev_b32_e32 v8, 16, v181
	v_and_b32_e32 v9, 0xffff0000, v181
	v_fma_f32 v18, v186, v18, v8
	v_fma_f32 v19, v187, v19, v9
	v_lshlrev_b32_e32 v8, 16, v182
	v_and_b32_e32 v9, 0xffff0000, v182
	v_fma_f32 v20, v188, v20, v8
	v_fma_f32 v21, v189, v21, v9
	v_lshlrev_b32_e32 v8, 16, v183
	v_and_b32_e32 v9, 0xffff0000, v183
	v_fma_f32 v22, v190, v22, v8
	v_fma_f32 v23, v191, v23, v9
	v_cvt_pk_bf16_f32 v4, v16, v17
	v_cvt_pk_bf16_f32 v5, v18, v19
	v_cvt_pk_bf16_f32 v6, v20, v21
	v_cvt_pk_bf16_f32 v7, v22, v23
	global_store_dwordx4 v11, v[4:7], s[96:97]
	s_waitcnt vmcnt(15)
	v_add_u32_e32 v11, s8, v11
	v_lshlrev_b32_e32 v8, 16, v192
	v_and_b32_e32 v9, 0xffff0000, v192
	v_fma_f32 v16, v196, v16, v8
	v_fma_f32 v17, v197, v17, v9
	v_lshlrev_b32_e32 v8, 16, v193
	v_and_b32_e32 v9, 0xffff0000, v193
	v_fma_f32 v18, v198, v18, v8
	v_fma_f32 v19, v199, v19, v9
	v_lshlrev_b32_e32 v8, 16, v194
	v_and_b32_e32 v9, 0xffff0000, v194
	v_fma_f32 v20, v200, v20, v8
	v_fma_f32 v21, v201, v21, v9
	v_lshlrev_b32_e32 v8, 16, v195
	v_and_b32_e32 v9, 0xffff0000, v195
	v_fma_f32 v22, v202, v22, v8
	v_fma_f32 v23, v203, v23, v9
	v_cvt_pk_bf16_f32 v212, v16, v17
	v_cvt_pk_bf16_f32 v213, v18, v19
	v_cvt_pk_bf16_f32 v214, v20, v21
	v_cvt_pk_bf16_f32 v215, v22, v23
	global_store_dwordx4 v11, v[212:215], s[96:97]
	s_branch .LBB0_1275
.Lscanb_generic:
	v_lshl_or_b32 v1, s94, 9, v0
	s_mov_b32 s2, 0x20000
	v_cmp_gt_i32_e32 vcc, s2, v1
	s_and_saveexec_b64 s[4:5], vcc
	s_cbranch_execz .LBB0_1274
	v_readlane_b32 s8, v249, 2
	v_readlane_b32 s9, v249, 3
	s_lshl_b32 s2, s8, 9
	s_mov_b64 s[8:9], 0
	s_movk_i32 s10, 0x60
	v_mov_b32_e32 v15, 0
	s_mov_b32 s11, 0x10000
	s_mov_b32 s12, 0x1ffff
	v_mov_b32_e32 v38, 3
	v_mov_b32_e32 v39, 5
